# grid/XCD barrier spin loops poll back to back (s_sleep 1 between polls removed, 5 sites)
# speedup vs baseline: 1.0149x; 1.0120x over previous
; __device__ __forceinline__ unsigned xb_ld(unsigned* p)              { return __hip_atomic_load(p, __ATOMIC_RELAXED, __HIP_MEMORY_SCOPE_AGENT); }
; __device__ __forceinline__ void xcd_barrier_complete(unsigned* bar, unsigned x, unsigned& nloc, unsigned& nx) {
;     const unsigned G = gridDim.x * gridDim.y * gridDim.z;
;     unsigned sum, cnt, mine, sp = 0u;
;     for (;;) {
;         sum = 0u; cnt = 0u; mine = 0u;
; #pragma unroll
;         for (unsigned j = 0; j < 16; ++j) { const unsigned c = xb_ld(&bar[XB_XCNT(j)]); sum += c; cnt += (c > 0u) ? 1u : 0u; mine = (j == x) ? c : mine; }
;         if (sum == G) break;
;         __builtin_amdgcn_s_sleep(1);
;         if ((++sp & 255u) == 0u) { if (xb_ld(&bar[XB_TMO])) break; if (sp > XB_SPIN_CAP) { atomicAdd(&bar[XB_TMO], 1u); break; } }
;     }
;     nloc = mine > 0u ? mine : 1u; nx = cnt > 0u ? cnt : 1u;
; }
.LBB0_416:
	v_readlane_b32 s4, v255, 0
	v_readlane_b32 s5, v255, 1
	global_load_dword v11, v169, s[82:83] offset:1024 sc1
	global_load_dword v0, v169, s[82:83] offset:1280 sc1
	global_load_dword v1, v169, s[82:83] offset:1536 sc1
	global_load_dword v2, v169, s[82:83] offset:1792 sc1
	global_load_dword v3, v169, s[82:83] offset:2048 sc1
	global_load_dword v4, v169, s[82:83] offset:2304 sc1
	global_load_dword v5, v169, s[82:83] offset:2560 sc1
	global_load_dword v6, v169, s[82:83] offset:2816 sc1
	global_load_dword v7, v169, s[82:83] offset:3072 sc1
	global_load_dword v8, v169, s[82:83] offset:3328 sc1
	global_load_dword v9, v169, s[82:83] offset:3584 sc1
	global_load_dword v10, v169, s[82:83] offset:3840 sc1
	global_load_dword v12, v169, s[4:5] sc1
	v_readlane_b32 s4, v255, 2
	v_readlane_b32 s5, v255, 3
	s_mov_b64 s[6:7], -1
	s_waitcnt vmcnt(11)
	v_add_u32_e32 v16, v0, v11
	s_nop 1
	global_load_dword v13, v169, s[4:5] sc1
	v_readlane_b32 s4, v255, 4
	v_readlane_b32 s5, v255, 5
	s_waitcnt vmcnt(11)
	v_add_u32_e32 v16, v16, v1
	s_waitcnt vmcnt(10)
	v_add_u32_e32 v16, v16, v2
	s_waitcnt vmcnt(9)
	v_add_u32_e32 v16, v16, v3
	s_waitcnt vmcnt(8)
	v_add_u32_e32 v16, v16, v4
	s_waitcnt vmcnt(7)
	v_add_u32_e32 v16, v16, v5
	global_load_dword v14, v169, s[4:5] sc1
	v_readlane_b32 s4, v255, 6
	v_readlane_b32 s5, v255, 7
	s_waitcnt vmcnt(7)
	v_add_u32_e32 v16, v16, v6
	s_waitcnt vmcnt(6)
	v_add_u32_e32 v16, v16, v7
	s_waitcnt vmcnt(5)
	v_add_u32_e32 v16, v16, v8
	s_waitcnt vmcnt(4)
	v_add_u32_e32 v16, v16, v9
	s_waitcnt vmcnt(3)
	v_add_u32_e32 v16, v16, v10
	global_load_dword v15, v169, s[4:5] sc1
	s_waitcnt vmcnt(3)
	v_add_u32_e32 v16, v16, v12
	s_mov_b64 s[4:5], -1
	s_waitcnt vmcnt(2)
	v_add_u32_e32 v16, v16, v13
	s_waitcnt vmcnt(1)
	v_add_u32_e32 v16, v16, v14
	s_waitcnt vmcnt(0)
	v_add_u32_e32 v16, v16, v15
	v_cmp_eq_u32_e32 vcc, s10, v16
	s_cbranch_vccnz .LBB0_415
	s_and_b32 s4, s11, 0xff
	s_cmp_eq_u32 s4, 0
	s_mov_b64 s[4:5], -1
	s_mov_b64 s[8:9], -1
	s_cbranch_scc1 .LBB0_420
	s_and_b64 vcc, exec, s[8:9]
	s_cbranch_vccz .LBB0_415

; __device__ __forceinline__ unsigned xb_ld(unsigned* p)              { return __hip_atomic_load(p, __ATOMIC_RELAXED, __HIP_MEMORY_SCOPE_AGENT); }
; __device__ __forceinline__ unsigned xb_add(unsigned* p, unsigned v) { return __hip_atomic_fetch_add(p, v, __ATOMIC_RELAXED, __HIP_MEMORY_SCOPE_AGENT); }
; #define XB_SPIN(cond, bar) do { unsigned _sp = 0; while (cond) { __builtin_amdgcn_s_sleep(1); \
;     if ((++_sp & 255u) == 0u) { if (xb_ld(&(bar)[XB_TMO])) break; if (_sp > XB_SPIN_CAP) { atomicAdd(&(bar)[XB_TMO], 1u); break; } } } } while (0)
; __device__ __forceinline__ void xcd_barrier(const XcdBarrier& b) {
;     ...
;         const unsigned old = xb_add(&bar[XB_XSUB(b.x)], 1u);
;         const unsigned gen = old / nloc;
;         if (old + 1u == (gen + 1u) * nloc) {
;             __builtin_amdgcn_fence(__ATOMIC_RELEASE, "agent");
;             asm volatile("s_waitcnt vmcnt(0)" ::: "memory");
;             const unsigned og = xb_add(&bar[XB_TOP], 1u);
;             const unsigned tg = og / nx;
;             if (og + 1u == (tg + 1u) * nx) xb_add(&bar[XB_TOPGEN], 1u);
;             else XB_SPIN(xb_ld(&bar[XB_TOPGEN]) == tg, bar);
;             __builtin_amdgcn_fence(__ATOMIC_ACQUIRE, "agent");
;             xb_add(&bar[XB_XGEN(b.x)], 1u);
;             asm volatile("s_waitcnt vmcnt(0)" ::: "memory");
;         } else {
;             XB_SPIN(xb_ld(&bar[XB_XGEN(b.x)]) == gen, bar);
;             __builtin_amdgcn_fence(__ATOMIC_ACQUIRE, "agent");
;             asm volatile("s_waitcnt vmcnt(0)" ::: "memory");
;         }
.LBB0_432:
	s_and_b32 s18, s22, 0xff
	s_mov_b64 s[16:17], -1
	s_cmp_lg_u32 s18, 0
	s_mov_b64 s[20:21], -1
	s_cbranch_scc0 .LBB0_435
	s_and_b64 vcc, exec, s[20:21]
	s_cbranch_vccz .LBB0_431

; __device__ __forceinline__ unsigned xb_ld(unsigned* p)              { return __hip_atomic_load(p, __ATOMIC_RELAXED, __HIP_MEMORY_SCOPE_AGENT); }
; __device__ __forceinline__ unsigned xb_add(unsigned* p, unsigned v) { return __hip_atomic_fetch_add(p, v, __ATOMIC_RELAXED, __HIP_MEMORY_SCOPE_AGENT); }
; #define XB_SPIN(cond, bar) do { unsigned _sp = 0; while (cond) { __builtin_amdgcn_s_sleep(1); \
;     if ((++_sp & 255u) == 0u) { if (xb_ld(&(bar)[XB_TMO])) break; if (_sp > XB_SPIN_CAP) { atomicAdd(&(bar)[XB_TMO], 1u); break; } } } } while (0)
; __device__ __forceinline__ void xcd_local_barrier(const XcdBarrier& b) {
;     asm volatile("s_waitcnt vmcnt(0)" ::: "memory");
;     __syncthreads();
;     if (threadIdx.x == 0) {
;         unsigned* bar = b.bar; const unsigned nloc = b.st[0];
;         const unsigned old = xb_add(&bar[XB_LSUB(b.x)], 1u), gen = old / nloc;
;         if (old + 1u == (gen + 1u) * nloc) xb_add(&bar[XB_LGEN(b.x)], 1u);
;         else XB_SPIN(xb_ld(&bar[XB_LGEN(b.x)]) == gen, bar);
;         __builtin_amdgcn_fence(__ATOMIC_ACQUIRE, "agent");
;         asm volatile("s_waitcnt vmcnt(0)" ::: "memory");
;     }
;     __syncthreads();
; }
.LBB0_450:
	s_and_b32 s16, s20, 0xff
	s_mov_b64 s[14:15], -1
	s_cmp_lg_u32 s16, 0
	s_mov_b64 s[18:19], -1
	s_cbranch_scc0 .LBB0_453
	s_and_b64 vcc, exec, s[18:19]
	s_cbranch_vccz .LBB0_449

; #define LAS __attribute__((address_space(3)))
; __global__ void __launch_bounds__(512, 2) fwd_kernel(Args args) {
;     ...
;             if (ph == 0) { cg::this_grid().sync(); xbar = xcd_barrier_post((unsigned*)(args.ws + WS_BAR), (volatile LAS unsigned*)(lds + 131072)); }
.LBB0_493:
	global_load_dword v1, v169, s[4:5] offset:32 sc1
	s_waitcnt vmcnt(0)
	v_and_b32_e32 v1, 0xffff0000, v1
	v_cmp_ne_u32_e32 vcc, v1, v0
	s_or_b64 s[6:7], vcc, s[6:7]
	s_andn2_b64 exec, exec, s[6:7]
	s_cbranch_execnz .LBB0_493
